# v41 + MLA half 2: row-sum add chain carried in v245 and issued behind each v_exp group in the QK gaps (same order)
# speedup vs baseline: 1.0136x; 1.0027x over previous
.LBB0_549:
	v_cndmask_b32_e64 v165, v165, v202, s[4:5]
	v_mul_f32_e32 v154, 0xbdd53b94, v165
	v_fmamk_f32 v202, v69, 0x3dd53b94, v154
	v_fmamk_f32 v215, v70, 0x3dd53b94, v154
	v_fmamk_f32 v155, v66, 0x3dd53b94, v154
	v_fmamk_f32 v156, v67, 0x3dd53b94, v154
	v_fmamk_f32 v157, v68, 0x3dd53b94, v154
	v_fmamk_f32 v216, v71, 0x3dd53b94, v154
	v_fmamk_f32 v217, v72, 0x3dd53b94, v154
	v_fmamk_f32 v218, v73, 0x3dd53b94, v154
	ds_read_b128 v[66:69], v174 offset:32768
	ds_read_b128 v[70:73], v174 offset:40960
	ds_read_b128 v[146:149], v176 offset:32768
	ds_read_b128 v[150:153], v176 offset:40960
	v_fmamk_f32 v224, v82, 0x3dd53b94, v154
	v_fmamk_f32 v225, v83, 0x3dd53b94, v154
	v_fmamk_f32 v226, v84, 0x3dd53b94, v154
	v_fmamk_f32 v227, v85, 0x3dd53b94, v154
	v_fmamk_f32 v228, v86, 0x3dd53b94, v154
	v_fmamk_f32 v229, v87, 0x3dd53b94, v154
	v_fmamk_f32 v230, v88, 0x3dd53b94, v154
	v_fmamk_f32 v231, v89, 0x3dd53b94, v154
	v_fmamk_f32 v234, v90, 0x3dd53b94, v154
	v_fmamk_f32 v235, v91, 0x3dd53b94, v154
	v_fmamk_f32 v236, v92, 0x3dd53b94, v154
	v_fmamk_f32 v237, v93, 0x3dd53b94, v154
	v_fmamk_f32 v238, v94, 0x3dd53b94, v154
	v_fmamk_f32 v239, v95, 0x3dd53b94, v154
	v_fmamk_f32 v240, v96, 0x3dd53b94, v154
	v_fmamk_f32 v241, v97, 0x3dd53b94, v154
	s_waitcnt lgkmcnt(0)
	v_mfma_f32_32x32x16_bf16 v[82:97], v[66:69], v[142:145], 0
	v_fmamk_f32 v232, v79, 0x3dd53b94, v154
	v_fmamk_f32 v233, v80, 0x3dd53b94, v154
	v_fmamk_f32 v219, v74, 0x3dd53b94, v154
	v_fmamk_f32 v220, v75, 0x3dd53b94, v154
	v_fmamk_f32 v221, v76, 0x3dd53b94, v154
	v_fmamk_f32 v222, v77, 0x3dd53b94, v154
	v_fmamk_f32 v223, v78, 0x3dd53b94, v154
	v_fmac_f32_e32 v154, 0x3dd53b94, v81
	v_mfma_f32_32x32x16_bf16 v[66:81], v[70:73], v[142:145], 0
	v_exp_f32_e32 v224, v224
	v_exp_f32_e32 v225, v225
	v_exp_f32_e32 v226, v226
	v_add_f32_e32 v245, 0, v224
	v_add_f32_e32 v245, v225, v245
	v_add_f32_e32 v245, v226, v245
	v_mfma_f32_32x32x16_bf16 v[82:97], v[146:149], v[138:141], v[82:97]
	v_exp_f32_e32 v227, v227
	v_exp_f32_e32 v228, v228
	v_add_f32_e32 v245, v227, v245
	v_add_f32_e32 v245, v228, v245
	v_mfma_f32_32x32x16_bf16 v[66:81], v[150:153], v[138:141], v[66:81]
	ds_read_b128 v[146:149], v178 offset:32768
	ds_read_b128 v[150:153], v178 offset:40960
	v_exp_f32_e32 v229, v229
	v_exp_f32_e32 v230, v230
	v_add_f32_e32 v245, v229, v245
	v_add_f32_e32 v245, v230, v245
	s_cmp_lg_u32 s98, 0
	s_cbranch_scc1 .Lattn_mla_nopf
	s_add_u32 s0, s38, s20
	s_addc_u32 s1, s39, s21
	s_add_u32 s100, s0, s42
	s_addc_u32 s101, s1, s43
	s_mov_b32 m0, s93
	v_lshl_add_u64 v[254:255], v[246:247], 0, s[100:101]
	global_load_lds_dwordx4 v[254:255], off
	s_add_u32 s100, s0, s46
	s_addc_u32 s101, s1, s47
	s_mov_b32 m0, s94
	v_lshl_add_u64 v[254:255], v[246:247], 0, s[100:101]
	global_load_lds_dwordx4 v[254:255], off
	s_add_u32 s100, s0, s44
	s_addc_u32 s101, s1, s45
	s_add_i32 s98, s89, s24
	s_mov_b32 m0, s98
	v_lshl_add_u64 v[254:255], v[248:249], 0, s[100:101]
	global_load_lds_dwordx4 v[254:255], off
	s_add_u32 s100, s0, s50
	s_addc_u32 s101, s1, s51
	s_add_i32 m0, s98, 0x2000
	v_lshl_add_u64 v[254:255], v[248:249], 0, s[100:101]
	global_load_lds_dwordx4 v[254:255], off
	s_add_u32 s0, s38, s88
	s_addc_u32 s1, s39, s87
	s_add_u32 s0, s0, s58
	s_addc_u32 s1, s1, s59
	s_mov_b32 m0, s95
	v_lshl_add_u64 v[254:255], v[250:251], 0, s[0:1]
	global_load_lds_dwordx4 v[254:255], off
.Lattn_mla_nopf:
	s_waitcnt lgkmcnt(0)
	v_mfma_f32_32x32x16_bf16 v[82:97], v[146:149], v[134:137], v[82:97]
	v_mfma_f32_32x32x16_bf16 v[66:81], v[150:153], v[134:137], v[66:81]
	ds_read_b128 v[146:149], v180 offset:32768
	ds_read_b128 v[150:153], v180 offset:40960
	v_exp_f32_e32 v231, v231
	v_exp_f32_e32 v234, v234
	v_exp_f32_e32 v235, v235
	v_add_f32_e32 v245, v231, v245
	v_add_f32_e32 v245, v234, v245
	v_add_f32_e32 v245, v235, v245
	s_waitcnt lgkmcnt(0)
	v_mfma_f32_32x32x16_bf16 v[82:97], v[146:149], v[130:133], v[82:97]
	v_mfma_f32_32x32x16_bf16 v[66:81], v[150:153], v[130:133], v[66:81]
	ds_read_b128 v[146:149], v182 offset:32768
	ds_read_b128 v[150:153], v182 offset:40960
	v_exp_f32_e32 v236, v236
	v_exp_f32_e32 v237, v237
	v_exp_f32_e32 v238, v238
	v_add_f32_e32 v245, v236, v245
	v_add_f32_e32 v245, v237, v245
	v_add_f32_e32 v245, v238, v245
	s_waitcnt lgkmcnt(0)
	v_mfma_f32_32x32x16_bf16 v[82:97], v[146:149], v[126:129], v[82:97]
	v_mfma_f32_32x32x16_bf16 v[66:81], v[150:153], v[126:129], v[66:81]
	ds_read_b128 v[146:149], v186 offset:32768
	ds_read_b128 v[150:153], v186 offset:40960
	v_exp_f32_e32 v239, v239
	v_exp_f32_e32 v240, v240
	v_exp_f32_e32 v241, v241
	v_add_f32_e32 v245, v239, v245
	v_add_f32_e32 v245, v240, v245
	v_add_f32_e32 v245, v241, v245
	s_waitcnt lgkmcnt(0)
	v_mfma_f32_32x32x16_bf16 v[82:97], v[146:149], v[122:125], v[82:97]
	v_mfma_f32_32x32x16_bf16 v[66:81], v[150:153], v[122:125], v[66:81]
	ds_read_b128 v[146:149], v188 offset:32768
	ds_read_b128 v[150:153], v188 offset:40960
	v_exp_f32_e32 v155, v155
	v_exp_f32_e32 v156, v156
	v_exp_f32_e32 v157, v157
	v_add_f32_e32 v245, v155, v245
	v_add_f32_e32 v245, v156, v245
	v_add_f32_e32 v245, v157, v245
	s_waitcnt lgkmcnt(0)
	v_mfma_f32_32x32x16_bf16 v[82:97], v[146:149], v[118:121], v[82:97]
	v_mfma_f32_32x32x16_bf16 v[66:81], v[150:153], v[118:121], v[66:81]
	ds_read_b128 v[146:149], v190 offset:32768
	ds_read_b128 v[150:153], v190 offset:40960
	v_exp_f32_e32 v202, v202
	v_exp_f32_e32 v215, v215
	v_exp_f32_e32 v216, v216
	v_add_f32_e32 v245, v202, v245
	v_add_f32_e32 v245, v215, v245
	v_add_f32_e32 v245, v216, v245
	s_waitcnt lgkmcnt(0)
	v_mfma_f32_32x32x16_bf16 v[82:97], v[146:149], v[114:117], v[82:97]
	v_mfma_f32_32x32x16_bf16 v[66:81], v[150:153], v[114:117], v[66:81]
	ds_read_b128 v[146:149], v192
	ds_read_b128 v[150:153], v192 offset:4096
	v_exp_f32_e32 v217, v217
	v_exp_f32_e32 v218, v218
	v_exp_f32_e32 v219, v219
	v_add_f32_e32 v245, v217, v245
	v_add_f32_e32 v245, v218, v245
	v_add_f32_e32 v245, v219, v245
	s_waitcnt lgkmcnt(0)
	v_mfma_f32_32x32x16_bf16 v[82:97], v[146:149], v[110:113], v[82:97]
	v_mfma_f32_32x32x16_bf16 v[66:81], v[150:153], v[110:113], v[66:81]
	ds_read_b128 v[146:149], v194
	ds_read_b128 v[150:153], v194 offset:4096
	v_exp_f32_e32 v220, v220
	v_exp_f32_e32 v221, v221
	v_exp_f32_e32 v222, v222
	v_add_f32_e32 v245, v220, v245
	v_add_f32_e32 v245, v221, v245
	v_add_f32_e32 v245, v222, v245
	s_waitcnt lgkmcnt(0)
	v_mfma_f32_32x32x16_bf16 v[82:97], v[146:149], v[106:109], v[82:97]
	v_mfma_f32_32x32x16_bf16 v[66:81], v[150:153], v[106:109], v[66:81]
	ds_read_b128 v[146:149], v196
	ds_read_b128 v[150:153], v196 offset:4096
	v_exp_f32_e32 v223, v223
	v_exp_f32_e32 v242, v232
	v_exp_f32_e32 v243, v233
	v_add_f32_e32 v245, v223, v245
	v_add_f32_e32 v245, v242, v245
	v_add_f32_e32 v245, v243, v245
	s_waitcnt lgkmcnt(0)
	v_mfma_f32_32x32x16_bf16 v[82:97], v[146:149], v[102:105], v[82:97]
	v_mfma_f32_32x32x16_bf16 v[66:81], v[150:153], v[102:105], v[66:81]
	ds_read_b128 v[146:149], v199
	ds_read_b128 v[150:153], v199 offset:4096
	v_exp_f32_e32 v244, v154
	s_waitcnt lgkmcnt(0)
	v_mfma_f32_32x32x16_bf16 v[82:97], v[146:149], v[98:101], v[82:97]
	v_mfma_f32_32x32x16_bf16 v[66:81], v[150:153], v[98:101], v[66:81]
	v_add_f32_e32 v232, v244, v245
	v_mov_b32_e32 v233, v232
	s_nop 1
	v_permlane32_swap_b32_e32 v232, v233
	v_cvt_pk_bf16_f32 v146, v224, v225
	v_cvt_pk_bf16_f32 v147, v226, v227
	v_cvt_pk_bf16_f32 v148, v228, v229
	v_cvt_pk_bf16_f32 v149, v230, v231
	v_cvt_pk_bf16_f32 v150, v234, v235
	v_cvt_pk_bf16_f32 v151, v236, v237
	v_cvt_pk_bf16_f32 v152, v238, v239
	v_cvt_pk_bf16_f32 v153, v240, v241
	v_cvt_pk_bf16_f32 v154, v155, v156
	v_cvt_pk_bf16_f32 v155, v157, v202
	v_cvt_pk_bf16_f32 v156, v215, v216
	v_cvt_pk_bf16_f32 v157, v217, v218
	v_cvt_pk_bf16_f32 v216, v219, v220
	v_cvt_pk_bf16_f32 v217, v221, v222
	v_cvt_pk_bf16_f32 v218, v223, v242
	v_cvt_pk_bf16_f32 v219, v243, v244
	s_nop 0
	v_permlane32_swap_b32_e32 v146, v148
	v_permlane32_swap_b32_e32 v147, v149
	v_permlane32_swap_b32_e32 v150, v152
	v_permlane32_swap_b32_e32 v151, v153
	v_permlane32_swap_b32_e32 v154, v156
	v_permlane32_swap_b32_e32 v155, v157
	v_permlane32_swap_b32_e32 v216, v218
	v_permlane32_swap_b32_e32 v217, v219
	v_lshl_add_u32 v242, s23, 14, v200
	ds_read_b64_tr_b16 v[220:221], v242 offset:0
	ds_read_b64_tr_b16 v[222:223], v242 offset:0x800
	ds_read_b64_tr_b16 v[224:225], v242 offset:0x1000
	ds_read_b64_tr_b16 v[226:227], v242 offset:0x1800
	ds_read_b64_tr_b16 v[228:229], v242 offset:0x2000
	ds_read_b64_tr_b16 v[230:231], v242 offset:0x2800
	ds_read_b64_tr_b16 v[234:235], v242 offset:0x3000
	ds_read_b64_tr_b16 v[236:237], v242 offset:0x3800
	s_waitcnt lgkmcnt(0)
	s_nop 0
	v_mfma_f32_32x32x16_bf16 v[2:17], v[146:149], v[220:223], v[2:17]
	ds_read_b64_tr_b16 v[220:221], v242 offset:0x200
	ds_read_b64_tr_b16 v[222:223], v242 offset:0xa00
	v_max_f32_e32 v202, v83, v83
	v_max_f32_e32 v215, v82, v82
	v_max_f32_e32 v202, v215, v202
	v_max3_f32 v202, v202, v84, v85
	v_max3_f32 v202, v202, v86, v87
	v_mfma_f32_32x32x16_bf16 v[2:17], v[150:153], v[224:227], v[2:17]
	ds_read_b64_tr_b16 v[224:225], v242 offset:0x1200
	ds_read_b64_tr_b16 v[226:227], v242 offset:0x1a00
	v_max3_f32 v202, v202, v88, v89
	v_max3_f32 v202, v202, v90, v91
	v_max3_f32 v202, v202, v92, v93
	v_max3_f32 v202, v202, v94, v95
	v_max3_f32 v202, v202, v96, v97
	v_mfma_f32_32x32x16_bf16 v[2:17], v[154:157], v[228:231], v[2:17]
	ds_read_b64_tr_b16 v[228:229], v242 offset:0x2200
	ds_read_b64_tr_b16 v[230:231], v242 offset:0x2a00
	ds_read_b64_tr_b16 v[238:239], v242 offset:0x3200
	ds_read_b64_tr_b16 v[240:241], v242 offset:0x3a00
	s_waitcnt lgkmcnt(0)
	v_mfma_f32_32x32x16_bf16 v[2:17], v[216:219], v[234:237], v[2:17]
	v_mfma_f32_32x32x16_bf16 v[50:65], v[146:149], v[220:223], v[50:65]
	v_max3_f32 v202, v202, v66, v67
	v_max3_f32 v202, v202, v68, v69
	v_max3_f32 v202, v202, v70, v71
	v_max3_f32 v202, v202, v72, v73
	v_max3_f32 v202, v202, v74, v75
	v_max3_f32 v202, v202, v76, v77
	v_max3_f32 v202, v202, v78, v79
	v_mfma_f32_32x32x16_bf16 v[50:65], v[150:153], v[224:227], v[50:65]
	v_max3_f32 v202, v202, v80, v81
	v_mov_b32_e32 v215, v202
	s_nop 1
	v_permlane32_swap_b32_e32 v202, v215
	v_max_f32_e32 v215, v215, v215
	v_max_f32_e32 v202, v202, v202
	v_max_f32_e32 v202, v202, v215
	v_max_f32_e32 v220, v165, v165
	v_sub_f32_e32 v215, v202, v165
	v_max_f32_e32 v202, v220, v202
	v_sub_f32_e32 v220, v165, v202
	v_mul_f32_e32 v220, 0x3dd53b94, v220
	v_mfma_f32_32x32x16_bf16 v[50:65], v[154:157], v[228:231], v[50:65]
	v_exp_f32_e32 v220, v220
	v_cmp_ge_f32_e32 vcc, s77, v215
	s_cmp_eq_u64 vcc, exec
	s_cselect_b64 s[4:5], -1, 0
	v_cndmask_b32_e64 v215, v220, 1.0, s[4:5]
	ds_read_b64_tr_b16 v[220:221], v242 offset:0x400
	ds_read_b64_tr_b16 v[222:223], v242 offset:0xc00
	ds_read_b64_tr_b16 v[224:225], v242 offset:0x1400
	v_mfma_f32_32x32x16_bf16 v[50:65], v[216:219], v[238:241], v[50:65]
	ds_read_b64_tr_b16 v[226:227], v242 offset:0x1c00
	ds_read_b64_tr_b16 v[228:229], v242 offset:0x2400
	ds_read_b64_tr_b16 v[230:231], v242 offset:0x2c00
	ds_read_b64_tr_b16 v[234:235], v242 offset:0x3400
	ds_read_b64_tr_b16 v[236:237], v242 offset:0x3c00
	s_waitcnt lgkmcnt(0)
	v_mfma_f32_32x32x16_bf16 v[34:49], v[146:149], v[220:223], v[34:49]
	ds_read_b64_tr_b16 v[220:221], v242 offset:0x600
	ds_read_b64_tr_b16 v[222:223], v242 offset:0xe00
	v_mfma_f32_32x32x16_bf16 v[34:49], v[150:153], v[224:227], v[34:49]
	ds_read_b64_tr_b16 v[224:225], v242 offset:0x1600
	ds_read_b64_tr_b16 v[226:227], v242 offset:0x1e00
	v_mfma_f32_32x32x16_bf16 v[34:49], v[154:157], v[228:231], v[34:49]
	ds_read_b64_tr_b16 v[228:229], v242 offset:0x2600
	ds_read_b64_tr_b16 v[230:231], v242 offset:0x2e00
	ds_read_b64_tr_b16 v[238:239], v242 offset:0x3600
	ds_read_b64_tr_b16 v[240:241], v242 offset:0x3e00
	s_waitcnt lgkmcnt(0)
	v_mfma_f32_32x32x16_bf16 v[34:49], v[216:219], v[234:237], v[34:49]
	v_mfma_f32_32x32x16_bf16 v[18:33], v[146:149], v[220:223], v[18:33]
	v_cmp_gt_f32_e32 vcc, 1.0, v215
	v_mfma_f32_32x32x16_bf16 v[18:33], v[150:153], v[224:227], v[18:33]
	v_mfma_f32_32x32x16_bf16 v[18:33], v[154:157], v[228:231], v[18:33]
	v_mfma_f32_32x32x16_bf16 v[18:33], v[216:219], v[238:241], v[18:33]
	s_cbranch_vccz .LBB0_553
	s_and_saveexec_b64 s[0:1], s[2:3]
	ds_write_b32 v170, v215 offset:128
	s_or_b64 exec, exec, s[0:1]
	s_waitcnt lgkmcnt(0)
	ds_read_b128 v[146:149], v158 offset:224
	ds_read_b128 v[150:153], v158 offset:192
	ds_read_b128 v[154:157], v158 offset:160
	ds_read_b128 v[216:219], v158 offset:128
	s_waitcnt lgkmcnt(0)
	v_pk_mul_f32 v[16:17], v[16:17], v[148:149]
	v_pk_mul_f32 v[12:13], v[12:13], v[152:153]
	v_pk_mul_f32 v[8:9], v[8:9], v[156:157]
	v_pk_mul_f32 v[4:5], v[4:5], v[218:219]
	v_pk_mul_f32 v[14:15], v[14:15], v[146:147]
	v_pk_mul_f32 v[10:11], v[10:11], v[150:151]
	v_pk_mul_f32 v[6:7], v[6:7], v[154:155]
	v_pk_mul_f32 v[2:3], v[2:3], v[216:217]
	v_pk_mul_f32 v[64:65], v[64:65], v[148:149]
	v_pk_mul_f32 v[60:61], v[60:61], v[152:153]
	v_pk_mul_f32 v[56:57], v[56:57], v[156:157]
	v_pk_mul_f32 v[52:53], v[52:53], v[218:219]
	v_pk_mul_f32 v[62:63], v[62:63], v[146:147]
	v_pk_mul_f32 v[58:59], v[58:59], v[150:151]
	v_pk_mul_f32 v[54:55], v[54:55], v[154:155]
	v_pk_mul_f32 v[50:51], v[50:51], v[216:217]
	v_pk_mul_f32 v[48:49], v[48:49], v[148:149]
	v_pk_mul_f32 v[44:45], v[44:45], v[152:153]
	v_pk_mul_f32 v[40:41], v[40:41], v[156:157]
	v_pk_mul_f32 v[36:37], v[36:37], v[218:219]
	v_pk_mul_f32 v[46:47], v[46:47], v[146:147]
	v_pk_mul_f32 v[42:43], v[42:43], v[150:151]
	v_pk_mul_f32 v[38:39], v[38:39], v[154:155]
	v_pk_mul_f32 v[34:35], v[34:35], v[216:217]
	v_pk_mul_f32 v[32:33], v[32:33], v[148:149]
	v_pk_mul_f32 v[28:29], v[28:29], v[152:153]
	v_pk_mul_f32 v[24:25], v[24:25], v[156:157]
	v_pk_mul_f32 v[20:21], v[20:21], v[218:219]
	v_pk_mul_f32 v[30:31], v[30:31], v[146:147]
	v_pk_mul_f32 v[26:27], v[26:27], v[150:151]
	v_pk_mul_f32 v[22:23], v[22:23], v[154:155]
	v_pk_mul_f32 v[18:19], v[18:19], v[216:217]
